# RS4+prio+V4opt, DMA blocks without s_nop (m0 write placed ahead of the two fragment reads)
# speedup vs baseline: 1.0314x; 1.0020x over previous
.Lv4_cont_h1:
	v_add_f32_e32 v224, v224, v188
	s_barrier
	s_setprio 0
	s_waitcnt lgkmcnt(2)
	v_mfma_f32_32x32x16_bf16 v[4:19], v[152:155], v[184:187], v[4:19]
	ds_read_b64_tr_b16 v[156:157], v3 offset:33792
	ds_read_b64_tr_b16 v[158:159], v3 offset:37888
	s_waitcnt lgkmcnt(2)
	v_mfma_f32_32x32x16_bf16 v[116:131], v[152:155], v[180:183], v[116:131]
	s_add_i32 m0, s80, 0x4000
	ds_read_b64_tr_b16 v[160:161], v3 offset:34304
	ds_read_b64_tr_b16 v[162:163], v3 offset:38400
	global_load_lds_dwordx4 v200, s[86:87]
	s_waitcnt lgkmcnt(2)
	v_mfma_f32_32x32x16_bf16 v[100:115], v[152:155], v[156:159], v[100:115]
	ds_read_b64_tr_b16 v[156:157], v3 offset:34816
	ds_read_b64_tr_b16 v[158:159], v3 offset:38912
	s_waitcnt lgkmcnt(2)
	v_mfma_f32_32x32x16_bf16 v[84:99], v[152:155], v[160:163], v[84:99]
	s_add_i32 m0, s81, 0x10000
	ds_read_b64_tr_b16 v[160:161], v3 offset:35328
	ds_read_b64_tr_b16 v[162:163], v3 offset:39424
	global_load_lds_dwordx4 v204, s[2:3]
	s_waitcnt lgkmcnt(2)
	v_mfma_f32_32x32x16_bf16 v[68:83], v[152:155], v[156:159], v[68:83]
	ds_read_b64_tr_b16 v[156:157], v3 offset:35840
	ds_read_b64_tr_b16 v[158:159], v3 offset:39936
	s_waitcnt lgkmcnt(2)
	v_mfma_f32_32x32x16_bf16 v[52:67], v[152:155], v[160:163], v[52:67]
	s_add_i32 m0, s81, 0x10400
	ds_read_b64_tr_b16 v[160:161], v3 offset:36352
	ds_read_b64_tr_b16 v[162:163], v3 offset:40448
	s_add_u32 s2, s2, 0x80
	s_addc_u32 s3, s3, 0
	global_load_lds_dwordx4 v204, s[2:3]
	s_waitcnt lgkmcnt(2)
	v_mfma_f32_32x32x16_bf16 v[36:51], v[152:155], v[156:159], v[36:51]
	ds_read_b64_tr_b16 v[156:157], v3 offset:40960
	ds_read_b64_tr_b16 v[158:159], v3 offset:45056
	s_waitcnt lgkmcnt(2)
	v_mfma_f32_32x32x16_bf16 v[20:35], v[152:155], v[160:163], v[20:35]
	s_add_i32 m0, s81, 0x10800
	ds_read_b64_tr_b16 v[152:153], v3 offset:41472
	ds_read_b64_tr_b16 v[154:155], v3 offset:45568
	s_add_u32 s2, s2, 0x80
	s_addc_u32 s3, s3, 0
	global_load_lds_dwordx4 v204, s[2:3]
	s_waitcnt lgkmcnt(2)
	v_mfma_f32_32x32x16_bf16 v[4:19], v[148:151], v[156:159], v[4:19]
	ds_read_b64_tr_b16 v[156:157], v3 offset:41984
	ds_read_b64_tr_b16 v[158:159], v3 offset:46080
	s_waitcnt lgkmcnt(2)
	v_mfma_f32_32x32x16_bf16 v[116:131], v[148:151], v[152:155], v[116:131]
	s_add_i32 m0, s81, 0x10c00
	ds_read_b64_tr_b16 v[152:153], v3 offset:42496
	ds_read_b64_tr_b16 v[154:155], v3 offset:46592
	s_add_u32 s2, s2, 0x80
	s_addc_u32 s3, s3, 0
	global_load_lds_dwordx4 v204, s[2:3]
	s_waitcnt lgkmcnt(2)
	v_mfma_f32_32x32x16_bf16 v[100:115], v[148:151], v[156:159], v[100:115]
	ds_read_b64_tr_b16 v[156:157], v3 offset:43008
	ds_read_b64_tr_b16 v[158:159], v3 offset:47104
	s_waitcnt lgkmcnt(2)
	v_mfma_f32_32x32x16_bf16 v[84:99], v[148:151], v[152:155], v[84:99]
	ds_read_b64_tr_b16 v[152:153], v3 offset:43520
	ds_read_b64_tr_b16 v[154:155], v3 offset:47616
	s_waitcnt lgkmcnt(2)
	v_mfma_f32_32x32x16_bf16 v[68:83], v[148:151], v[156:159], v[68:83]
	ds_read_b64_tr_b16 v[156:157], v3 offset:44032
	ds_read_b64_tr_b16 v[158:159], v3 offset:48128
	s_waitcnt lgkmcnt(2)
	v_mfma_f32_32x32x16_bf16 v[52:67], v[148:151], v[152:155], v[52:67]
	ds_read_b64_tr_b16 v[152:153], v3 offset:44544
	ds_read_b64_tr_b16 v[154:155], v3 offset:48640
	s_waitcnt lgkmcnt(2)
	v_mfma_f32_32x32x16_bf16 v[36:51], v[148:151], v[156:159], v[36:51]
	s_waitcnt lgkmcnt(0)
	v_mfma_f32_32x32x16_bf16 v[20:35], v[148:151], v[152:155], v[20:35]
	s_barrier
	s_setprio 1
	ds_read_b128 v[180:183], v225 offset:4096
	ds_read_b128 v[184:187], v226 offset:4096
	s_waitcnt lgkmcnt(1)
	v_mfma_i32_32x32x32_i8 v[148:163], v[180:183], v[164:167], v[132:147]
	ds_read_b128 v[180:183], v227 offset:4096
	s_waitcnt lgkmcnt(1)
	v_mfma_i32_32x32x32_i8 v[148:163], v[184:187], v[168:171], v[148:163]
	ds_read_b128 v[188:191], v228 offset:4096
	s_waitcnt lgkmcnt(1)
	v_mfma_i32_32x32x32_i8 v[148:163], v[180:183], v[172:175], v[148:163]
	ds_read_b64_tr_b16 v[184:185], v3 offset:49152
	ds_read_b64_tr_b16 v[186:187], v3 offset:53248
	s_waitcnt lgkmcnt(2)
	v_mfma_i32_32x32x32_i8 v[148:163], v[188:191], v[176:179], v[148:163]
	ds_read_b64_tr_b16 v[180:181], v3 offset:49664
	ds_read_b64_tr_b16 v[182:183], v3 offset:53760
	s_nop 7
	v_mul_f32_e32 v189, v221, v207
	v_fma_f32 v190, s100, v189, v255
	v_fma_f32 v148, v148, v189, -v190
	v_fma_f32 v149, v149, v189, -v190
	v_exp_f32_e32 v148, v148
	v_fma_f32 v150, v150, v189, -v190
	v_exp_f32_e32 v149, v149
	v_fma_f32 v151, v151, v189, -v190
	v_exp_f32_e32 v150, v150
	v_fma_f32 v152, v152, v189, -v190
	v_exp_f32_e32 v151, v151
	v_fma_f32 v153, v153, v189, -v190
	v_exp_f32_e32 v152, v152
	v_fma_f32 v154, v154, v189, -v190
	v_exp_f32_e32 v153, v153
	v_fma_f32 v155, v155, v189, -v190
	v_exp_f32_e32 v154, v154
	v_fma_f32 v156, v156, v189, -v190
	v_exp_f32_e32 v155, v155
	v_fma_f32 v157, v157, v189, -v190
	v_exp_f32_e32 v156, v156
	v_fma_f32 v158, v158, v189, -v190
	v_exp_f32_e32 v157, v157
	v_fma_f32 v159, v159, v189, -v190
	v_exp_f32_e32 v158, v158
	v_fma_f32 v160, v160, v189, -v190
	v_exp_f32_e32 v159, v159
	v_fma_f32 v161, v161, v189, -v190
	v_exp_f32_e32 v160, v160
	v_fma_f32 v162, v162, v189, -v190
	v_exp_f32_e32 v161, v161
	v_fma_f32 v163, v163, v189, -v190
	v_exp_f32_e32 v162, v162
	v_exp_f32_e32 v163, v163
	v_add_f32_e32 v188, v148, v149
	v_add_f32_e32 v189, v150, v151
	v_add_f32_e32 v190, v152, v153
	v_add_f32_e32 v191, v154, v155
	v_add_f32_e32 v192, v156, v157
	v_add_f32_e32 v193, v158, v159
	v_add_f32_e32 v194, v160, v161
	v_add_f32_e32 v195, v162, v163
	v_add_f32_e32 v188, v188, v189
	v_add_f32_e32 v190, v190, v191
	v_add_f32_e32 v192, v192, v193
	v_add_f32_e32 v194, v194, v195
	v_add_f32_e32 v188, v188, v190
	v_add_f32_e32 v192, v192, v194
	v_add_f32_e32 v188, v188, v192
	v_cmp_lt_f32_e32 vcc, s101, v188
	v_cvt_pk_bf16_f32 v155, v154, v155
	v_cvt_pk_bf16_f32 v154, v152, v153
	v_cvt_pk_bf16_f32 v152, v148, v149
	v_cvt_pk_bf16_f32 v153, v150, v151
	v_cvt_pk_bf16_f32 v148, v156, v157
	v_cvt_pk_bf16_f32 v149, v158, v159
	v_cvt_pk_bf16_f32 v150, v160, v161
	v_cvt_pk_bf16_f32 v151, v162, v163
	s_cbranch_vccnz .Lv4_rare_h2

.Lv4_cont_h3:
	v_add_f32_e32 v224, v224, v188
	s_barrier
	s_setprio 0
	s_waitcnt lgkmcnt(2)
	v_mfma_f32_32x32x16_bf16 v[4:19], v[152:155], v[184:187], v[4:19]
	ds_read_b64_tr_b16 v[156:157], v222 offset:33792
	ds_read_b64_tr_b16 v[158:159], v222 offset:37888
	s_waitcnt lgkmcnt(2)
	v_mfma_f32_32x32x16_bf16 v[116:131], v[152:155], v[180:183], v[116:131]
	s_add_i32 m0, s83, 0
	ds_read_b64_tr_b16 v[160:161], v222 offset:34304
	ds_read_b64_tr_b16 v[162:163], v222 offset:38400
	global_load_lds_dwordx4 v200, s[86:87]
	s_waitcnt lgkmcnt(2)
	v_mfma_f32_32x32x16_bf16 v[100:115], v[152:155], v[156:159], v[100:115]
	ds_read_b64_tr_b16 v[156:157], v222 offset:34816
	ds_read_b64_tr_b16 v[158:159], v222 offset:38912
	s_waitcnt lgkmcnt(2)
	v_mfma_f32_32x32x16_bf16 v[84:99], v[152:155], v[160:163], v[84:99]
	s_add_i32 m0, s82, 0
	ds_read_b64_tr_b16 v[160:161], v222 offset:35328
	ds_read_b64_tr_b16 v[162:163], v222 offset:39424
	global_load_lds_dwordx4 v204, s[2:3]
	s_waitcnt lgkmcnt(2)
	v_mfma_f32_32x32x16_bf16 v[68:83], v[152:155], v[156:159], v[68:83]
	ds_read_b64_tr_b16 v[156:157], v222 offset:35840
	ds_read_b64_tr_b16 v[158:159], v222 offset:39936
	s_waitcnt lgkmcnt(2)
	v_mfma_f32_32x32x16_bf16 v[52:67], v[152:155], v[160:163], v[52:67]
	s_add_i32 m0, s82, 0x400
	ds_read_b64_tr_b16 v[160:161], v222 offset:36352
	ds_read_b64_tr_b16 v[162:163], v222 offset:40448
	s_add_u32 s2, s2, 0x80
	s_addc_u32 s3, s3, 0
	global_load_lds_dwordx4 v204, s[2:3]
	s_waitcnt lgkmcnt(2)
	v_mfma_f32_32x32x16_bf16 v[36:51], v[152:155], v[156:159], v[36:51]
	ds_read_b64_tr_b16 v[156:157], v222 offset:40960
	ds_read_b64_tr_b16 v[158:159], v222 offset:45056
	s_waitcnt lgkmcnt(2)
	v_mfma_f32_32x32x16_bf16 v[20:35], v[152:155], v[160:163], v[20:35]
	s_add_i32 m0, s82, 0x800
	ds_read_b64_tr_b16 v[152:153], v222 offset:41472
	ds_read_b64_tr_b16 v[154:155], v222 offset:45568
	s_add_u32 s2, s2, 0x80
	s_addc_u32 s3, s3, 0
	global_load_lds_dwordx4 v204, s[2:3]
	s_waitcnt lgkmcnt(2)
	v_mfma_f32_32x32x16_bf16 v[4:19], v[148:151], v[156:159], v[4:19]
	ds_read_b64_tr_b16 v[156:157], v222 offset:41984
	ds_read_b64_tr_b16 v[158:159], v222 offset:46080
	s_waitcnt lgkmcnt(2)
	v_mfma_f32_32x32x16_bf16 v[116:131], v[148:151], v[152:155], v[116:131]
	s_add_i32 m0, s82, 0xc00
	ds_read_b64_tr_b16 v[152:153], v222 offset:42496
	ds_read_b64_tr_b16 v[154:155], v222 offset:46592
	s_add_u32 s2, s2, 0x80
	s_addc_u32 s3, s3, 0
	global_load_lds_dwordx4 v204, s[2:3]
	s_waitcnt lgkmcnt(2)
	v_mfma_f32_32x32x16_bf16 v[100:115], v[148:151], v[156:159], v[100:115]
	ds_read_b64_tr_b16 v[156:157], v222 offset:43008
	ds_read_b64_tr_b16 v[158:159], v222 offset:47104
	s_waitcnt lgkmcnt(2)
	v_mfma_f32_32x32x16_bf16 v[84:99], v[148:151], v[152:155], v[84:99]
	ds_read_b64_tr_b16 v[152:153], v222 offset:43520
	ds_read_b64_tr_b16 v[154:155], v222 offset:47616
	s_waitcnt lgkmcnt(2)
	v_mfma_f32_32x32x16_bf16 v[68:83], v[148:151], v[156:159], v[68:83]
	ds_read_b64_tr_b16 v[156:157], v222 offset:44032
	ds_read_b64_tr_b16 v[158:159], v222 offset:48128
	s_waitcnt lgkmcnt(2)
	v_mfma_f32_32x32x16_bf16 v[52:67], v[148:151], v[152:155], v[52:67]
	ds_read_b64_tr_b16 v[152:153], v222 offset:44544
	ds_read_b64_tr_b16 v[154:155], v222 offset:48640
	s_waitcnt lgkmcnt(2)
	v_mfma_f32_32x32x16_bf16 v[36:51], v[148:151], v[156:159], v[36:51]
	s_waitcnt lgkmcnt(0)
	v_mfma_f32_32x32x16_bf16 v[20:35], v[148:151], v[152:155], v[20:35]
	s_barrier
	s_setprio 1
	ds_read_b128 v[180:183], v225 offset:20480
	ds_read_b128 v[184:187], v226 offset:20480
	s_waitcnt lgkmcnt(1)
	v_mfma_i32_32x32x32_i8 v[148:163], v[180:183], v[164:167], v[132:147]
	ds_read_b128 v[180:183], v227 offset:20480
	s_waitcnt lgkmcnt(1)
	v_mfma_i32_32x32x32_i8 v[148:163], v[184:187], v[168:171], v[148:163]
	ds_read_b128 v[188:191], v228 offset:20480
	s_waitcnt lgkmcnt(1)
	v_mfma_i32_32x32x32_i8 v[148:163], v[180:183], v[172:175], v[148:163]
	ds_read_b64_tr_b16 v[184:185], v222 offset:49152
	ds_read_b64_tr_b16 v[186:187], v222 offset:53248
	s_waitcnt lgkmcnt(2)
	v_mfma_i32_32x32x32_i8 v[148:163], v[188:191], v[176:179], v[148:163]
	ds_read_b64_tr_b16 v[180:181], v222 offset:49664
	ds_read_b64_tr_b16 v[182:183], v222 offset:53760
	s_nop 7
	v_mul_f32_e32 v189, v221, v236
	v_fma_f32 v190, s100, v189, v255
	v_fma_f32 v148, v148, v189, -v190
	v_fma_f32 v149, v149, v189, -v190
	v_exp_f32_e32 v148, v148
	v_fma_f32 v150, v150, v189, -v190
	v_exp_f32_e32 v149, v149
	v_fma_f32 v151, v151, v189, -v190
	v_exp_f32_e32 v150, v150
	v_fma_f32 v152, v152, v189, -v190
	v_exp_f32_e32 v151, v151
	v_fma_f32 v153, v153, v189, -v190
	v_exp_f32_e32 v152, v152
	v_fma_f32 v154, v154, v189, -v190
	v_exp_f32_e32 v153, v153
	v_fma_f32 v155, v155, v189, -v190
	v_exp_f32_e32 v154, v154
	v_fma_f32 v156, v156, v189, -v190
	v_exp_f32_e32 v155, v155
	v_fma_f32 v157, v157, v189, -v190
	v_exp_f32_e32 v156, v156
	v_fma_f32 v158, v158, v189, -v190
	v_exp_f32_e32 v157, v157
	v_fma_f32 v159, v159, v189, -v190
	v_exp_f32_e32 v158, v158
	v_fma_f32 v160, v160, v189, -v190
	v_exp_f32_e32 v159, v159
	v_fma_f32 v161, v161, v189, -v190
	v_exp_f32_e32 v160, v160
	v_fma_f32 v162, v162, v189, -v190
	v_exp_f32_e32 v161, v161
	v_fma_f32 v163, v163, v189, -v190
	v_exp_f32_e32 v162, v162
	v_exp_f32_e32 v163, v163
	v_add_f32_e32 v188, v148, v149
	v_add_f32_e32 v189, v150, v151
	v_add_f32_e32 v190, v152, v153
	v_add_f32_e32 v191, v154, v155
	v_add_f32_e32 v192, v156, v157
	v_add_f32_e32 v193, v158, v159
	v_add_f32_e32 v194, v160, v161
	v_add_f32_e32 v195, v162, v163
	v_add_f32_e32 v188, v188, v189
	v_add_f32_e32 v190, v190, v191
	v_add_f32_e32 v192, v192, v193
	v_add_f32_e32 v194, v194, v195
	v_add_f32_e32 v188, v188, v190
	v_add_f32_e32 v192, v192, v194
	v_add_f32_e32 v188, v188, v192
	v_cmp_lt_f32_e32 vcc, s101, v188
	v_cvt_pk_bf16_f32 v155, v154, v155
	v_cvt_pk_bf16_f32 v154, v152, v153
	v_cvt_pk_bf16_f32 v152, v148, v149
	v_cvt_pk_bf16_f32 v153, v150, v151
	v_cvt_pk_bf16_f32 v148, v156, v157
	v_cvt_pk_bf16_f32 v149, v158, v159
	v_cvt_pk_bf16_f32 v150, v160, v161
	v_cvt_pk_bf16_f32 v151, v162, v163
	s_cbranch_vccnz .Lv4_rare_h4
